# out-GEMM fused epilogue (bf16 residual path): the 16 residual tiles are staged with LDS-DMA into the idle GEMM stage area in one burst and read back with ds_read_b128, replacing 16 serialized HBM roun
# baseline (speedup 1.0000x reference)
; __device__ __forceinline__ float bflo(unsigned w) { return __uint_as_float(w << 16); }
; __device__ __forceinline__ float bfhi(unsigned w) { return __uint_as_float(w & 0xffff0000u); }
;     __device__ __forceinline__ void fused(f32x4 (&acc)[2][2][4][2], const Unit& u, int wr, int wc, int fr, int fq, LAS unsigned char* lds, int wid, int lane) const {
;     ...
;                 for (int ai = 0; ai < 2; ++ai)
; #pragma unroll
;                     for (int m = 0; m < 4; ++m) {
;                         const u32x4 xw = *(const u32x4*)(xin16 + (unsigned)((row0 + ai * 128 + m * 16) * DM + col));
;                         const f32x4 x0 = (f32x4){bflo(xw.x), bfhi(xw.x), bflo(xw.y), bfhi(xw.y)}, x1 = (f32x4){bflo(xw.z), bfhi(xw.z), bflo(xw.w), bfhi(xw.w)};
;                         acc[ai][bj][m][0] = x0 + g0 * acc[ai][bj][m][0]; acc[ai][bj][m][1] = x1 + g1 * acc[ai][bj][m][1];
;                         asm volatile("" : "+v"(acc[ai][bj][m][0]), "+v"(acc[ai][bj][m][1]));
;                     }
.LBB0_295:
	v_lshl_add_u64 v[52:53], v[64:65], 1, s[0:1]
	ds_read_b128 v[52:55], v210
	v_mov_b32_e32 v231, v65
	v_mov_b32_e32 v229, v65
	v_mov_b32_e32 v227, v65
	v_mov_b32_e32 v225, v65
	v_mov_b32_e32 v223, v65
	v_mov_b32_e32 v221, v65
	v_mov_b32_e32 v219, v65
	s_waitcnt vmcnt(0) lgkmcnt(0)
	v_lshlrev_b32_e32 v60, 16, v52
	v_and_b32_e32 v61, 0xffff0000, v52
	v_lshlrev_b32_e32 v52, 16, v53
	v_and_b32_e32 v53, 0xffff0000, v53
	v_lshlrev_b32_e32 v62, 16, v54
	v_and_b32_e32 v63, 0xffff0000, v54
	v_lshlrev_b32_e32 v54, 16, v55
	v_and_b32_e32 v55, 0xffff0000, v55
	v_pk_fma_f32 v[68:69], v[192:193], v[200:201], v[52:53]
	v_pk_fma_f32 v[66:67], v[190:191], v[198:199], v[60:61]
	v_pk_fma_f32 v[72:73], v[188:189], v[196:197], v[54:55]
	v_pk_fma_f32 v[70:71], v[186:187], v[194:195], v[62:63]
	v_lshl_add_u64 v[52:53], v[230:231], 1, s[0:1]
	ds_read_b128 v[52:55], v210 offset:1024
	s_waitcnt vmcnt(0) lgkmcnt(0)
	v_lshlrev_b32_e32 v60, 16, v52
	v_and_b32_e32 v61, 0xffff0000, v52
	v_lshlrev_b32_e32 v52, 16, v53
	v_and_b32_e32 v53, 0xffff0000, v53
	v_lshlrev_b32_e32 v62, 16, v54
	v_and_b32_e32 v63, 0xffff0000, v54
	v_lshlrev_b32_e32 v54, 16, v55
	v_and_b32_e32 v55, 0xffff0000, v55
	v_pk_fma_f32 v[76:77], v[184:185], v[200:201], v[52:53]
	v_pk_fma_f32 v[74:75], v[182:183], v[198:199], v[60:61]
	v_pk_fma_f32 v[80:81], v[180:181], v[196:197], v[54:55]
	v_pk_fma_f32 v[78:79], v[178:179], v[194:195], v[62:63]
	v_lshl_add_u64 v[52:53], v[228:229], 1, s[0:1]
	ds_read_b128 v[52:55], v210 offset:2048
	s_waitcnt vmcnt(0) lgkmcnt(0)
	v_lshlrev_b32_e32 v60, 16, v52
	v_and_b32_e32 v61, 0xffff0000, v52
	v_lshlrev_b32_e32 v52, 16, v53
	v_and_b32_e32 v53, 0xffff0000, v53
	v_lshlrev_b32_e32 v62, 16, v54
	v_and_b32_e32 v63, 0xffff0000, v54
	v_lshlrev_b32_e32 v54, 16, v55
	v_and_b32_e32 v55, 0xffff0000, v55
	v_pk_fma_f32 v[92:93], v[176:177], v[200:201], v[52:53]
	v_pk_fma_f32 v[90:91], v[174:175], v[198:199], v[60:61]
	v_pk_fma_f32 v[96:97], v[172:173], v[196:197], v[54:55]
	v_pk_fma_f32 v[94:95], v[170:171], v[194:195], v[62:63]
	v_lshl_add_u64 v[52:53], v[226:227], 1, s[0:1]
	ds_read_b128 v[52:55], v210 offset:3072
	s_waitcnt vmcnt(0) lgkmcnt(0)
	v_lshlrev_b32_e32 v60, 16, v52
	v_and_b32_e32 v61, 0xffff0000, v52
	v_lshlrev_b32_e32 v52, 16, v53
	v_and_b32_e32 v53, 0xffff0000, v53
	v_lshlrev_b32_e32 v82, 16, v54
	v_and_b32_e32 v83, 0xffff0000, v54
	v_lshlrev_b32_e32 v62, 16, v55
	v_and_b32_e32 v63, 0xffff0000, v55
	v_pk_fma_f32 v[54:55], v[168:169], v[200:201], v[52:53]
	v_pk_fma_f32 v[52:53], v[166:167], v[198:199], v[60:61]
	v_pk_fma_f32 v[62:63], v[164:165], v[196:197], v[62:63]
	v_pk_fma_f32 v[60:61], v[162:163], v[194:195], v[82:83]
	v_lshl_add_u64 v[82:83], v[224:225], 1, s[0:1]
	ds_read_b128 v[82:85], v210 offset:4096
	s_waitcnt vmcnt(0) lgkmcnt(0)
	v_lshlrev_b32_e32 v86, 16, v82
	v_and_b32_e32 v87, 0xffff0000, v82
	v_lshlrev_b32_e32 v82, 16, v83
	v_and_b32_e32 v83, 0xffff0000, v83
	v_lshlrev_b32_e32 v106, 16, v84
	v_and_b32_e32 v107, 0xffff0000, v84
	v_lshlrev_b32_e32 v88, 16, v85
	v_and_b32_e32 v89, 0xffff0000, v85
	v_pk_fma_f32 v[84:85], v[160:161], v[200:201], v[82:83]
	v_pk_fma_f32 v[82:83], v[158:159], v[198:199], v[86:87]
	v_pk_fma_f32 v[88:89], v[156:157], v[196:197], v[88:89]
	v_pk_fma_f32 v[86:87], v[154:155], v[194:195], v[106:107]
	v_lshl_add_u64 v[106:107], v[222:223], 1, s[0:1]
	ds_read_b128 v[106:109], v210 offset:5120
	s_waitcnt vmcnt(0) lgkmcnt(0)
	v_lshlrev_b32_e32 v110, 16, v106
	v_and_b32_e32 v111, 0xffff0000, v106
	v_lshlrev_b32_e32 v106, 16, v107
	v_and_b32_e32 v107, 0xffff0000, v107
	v_lshlrev_b32_e32 v114, 16, v108
	v_and_b32_e32 v115, 0xffff0000, v108
	v_lshlrev_b32_e32 v112, 16, v109
	v_and_b32_e32 v113, 0xffff0000, v109
	v_pk_fma_f32 v[108:109], v[152:153], v[200:201], v[106:107]
	v_pk_fma_f32 v[106:107], v[150:151], v[198:199], v[110:111]
	v_pk_fma_f32 v[112:113], v[148:149], v[196:197], v[112:113]
	v_pk_fma_f32 v[110:111], v[146:147], v[194:195], v[114:115]
	v_lshl_add_u64 v[114:115], v[220:221], 1, s[0:1]
	ds_read_b128 v[114:117], v210 offset:6144
	s_waitcnt vmcnt(0) lgkmcnt(0)
	v_lshlrev_b32_e32 v118, 16, v114
	v_and_b32_e32 v119, 0xffff0000, v114
	v_lshlrev_b32_e32 v114, 16, v115
	v_and_b32_e32 v115, 0xffff0000, v115
	v_lshlrev_b32_e32 v122, 16, v116
	v_and_b32_e32 v123, 0xffff0000, v116
	v_lshlrev_b32_e32 v120, 16, v117
	v_and_b32_e32 v121, 0xffff0000, v117
	v_pk_fma_f32 v[116:117], v[144:145], v[200:201], v[114:115]
	v_pk_fma_f32 v[114:115], v[142:143], v[198:199], v[118:119]
	v_pk_fma_f32 v[120:121], v[140:141], v[196:197], v[120:121]
	v_pk_fma_f32 v[118:119], v[138:139], v[194:195], v[122:123]
	v_lshl_add_u64 v[122:123], v[218:219], 1, s[0:1]
	ds_read_b128 v[122:125], v210 offset:7168
	s_waitcnt vmcnt(0) lgkmcnt(0)
	v_lshlrev_b32_e32 v126, 16, v122
	v_and_b32_e32 v127, 0xffff0000, v122
	v_lshlrev_b32_e32 v122, 16, v123
	v_and_b32_e32 v123, 0xffff0000, v123
	v_lshlrev_b32_e32 v138, 16, v124
	v_and_b32_e32 v139, 0xffff0000, v124
	v_lshlrev_b32_e32 v128, 16, v125
	v_and_b32_e32 v129, 0xffff0000, v125
	v_pk_fma_f32 v[124:125], v[136:137], v[200:201], v[122:123]
	v_pk_fma_f32 v[122:123], v[134:135], v[198:199], v[126:127]
	v_pk_fma_f32 v[128:129], v[132:133], v[196:197], v[128:129]
	v_pk_fma_f32 v[126:127], v[130:131], v[194:195], v[138:139]
	s_nop 0

; __device__ __forceinline__ float bflo(unsigned w) { return __uint_as_float(w << 16); }
; __device__ __forceinline__ float bfhi(unsigned w) { return __uint_as_float(w & 0xffff0000u); }
;     __device__ __forceinline__ void fused(f32x4 (&acc)[2][2][4][2], const Unit& u, int wr, int wc, int fr, int fq, LAS unsigned char* lds, int wid, int lane) const {
;     ...
;                 for (int ai = 0; ai < 2; ++ai)
; #pragma unroll
;                     for (int m = 0; m < 4; ++m) {
;                         const u32x4 xw = *(const u32x4*)(xin16 + (unsigned)((row0 + ai * 128 + m * 16) * DM + col));
;                         const f32x4 x0 = (f32x4){bflo(xw.x), bfhi(xw.x), bflo(xw.y), bfhi(xw.y)}, x1 = (f32x4){bflo(xw.z), bfhi(xw.z), bflo(xw.w), bfhi(xw.w)};
;                         acc[ai][bj][m][0] = x0 + g0 * acc[ai][bj][m][0]; acc[ai][bj][m][1] = x1 + g1 * acc[ai][bj][m][1];
;                         asm volatile("" : "+v"(acc[ai][bj][m][0]), "+v"(acc[ai][bj][m][1]));
;                     }
.LBB0_298:
	v_lshl_add_u64 v[130:131], v[64:65], 1, s[0:1]
	ds_read_b128 v[130:133], v211
	v_mov_b32_e32 v229, v65
	v_mov_b32_e32 v227, v65
	v_mov_b32_e32 v225, v65
	v_mov_b32_e32 v223, v65
	v_mov_b32_e32 v221, v65
	v_mov_b32_e32 v219, v65
	v_mov_b32_e32 v217, v65
	s_waitcnt vmcnt(0) lgkmcnt(0)
	v_lshlrev_b32_e32 v134, 16, v130
	v_and_b32_e32 v135, 0xffff0000, v130
	v_lshlrev_b32_e32 v130, 16, v131
	v_and_b32_e32 v131, 0xffff0000, v131
	v_lshlrev_b32_e32 v138, 16, v132
	v_and_b32_e32 v139, 0xffff0000, v132
	v_lshlrev_b32_e32 v136, 16, v133
	v_and_b32_e32 v137, 0xffff0000, v133
	v_pk_fma_f32 v[132:133], v[104:105], v[200:201], v[130:131]
	v_pk_fma_f32 v[130:131], v[102:103], v[198:199], v[134:135]
	v_pk_fma_f32 v[136:137], v[100:101], v[196:197], v[136:137]
	v_pk_fma_f32 v[134:135], v[98:99], v[194:195], v[138:139]
	v_lshl_add_u64 v[98:99], v[228:229], 1, s[0:1]
	ds_read_b128 v[98:101], v211 offset:1024
	s_waitcnt vmcnt(0) lgkmcnt(0)
	v_lshlrev_b32_e32 v102, 16, v98
	v_and_b32_e32 v103, 0xffff0000, v98
	v_lshlrev_b32_e32 v98, 16, v99
	v_and_b32_e32 v99, 0xffff0000, v99
	v_lshlrev_b32_e32 v104, 16, v100
	v_and_b32_e32 v105, 0xffff0000, v100
	v_lshlrev_b32_e32 v100, 16, v101
	v_and_b32_e32 v101, 0xffff0000, v101
	v_pk_fma_f32 v[140:141], v[58:59], v[200:201], v[98:99]
	v_pk_fma_f32 v[138:139], v[56:57], v[198:199], v[102:103]
	v_pk_fma_f32 v[144:145], v[50:51], v[196:197], v[100:101]
	v_pk_fma_f32 v[142:143], v[48:49], v[194:195], v[104:105]
	v_lshl_add_u64 v[48:49], v[226:227], 1, s[0:1]
	ds_read_b128 v[48:51], v211 offset:2048
	s_waitcnt vmcnt(0) lgkmcnt(0)
	v_lshlrev_b32_e32 v56, 16, v48
	v_and_b32_e32 v57, 0xffff0000, v48
	v_lshlrev_b32_e32 v48, 16, v49
	v_and_b32_e32 v49, 0xffff0000, v49
	v_lshlrev_b32_e32 v58, 16, v50
	v_and_b32_e32 v59, 0xffff0000, v50
	v_lshlrev_b32_e32 v50, 16, v51
	v_and_b32_e32 v51, 0xffff0000, v51
	v_pk_fma_f32 v[148:149], v[46:47], v[200:201], v[48:49]
	v_pk_fma_f32 v[146:147], v[44:45], v[198:199], v[56:57]
	v_pk_fma_f32 v[152:153], v[42:43], v[196:197], v[50:51]
	v_pk_fma_f32 v[150:151], v[40:41], v[194:195], v[58:59]
	v_lshl_add_u64 v[40:41], v[224:225], 1, s[0:1]
	ds_read_b128 v[40:43], v211 offset:3072
	s_waitcnt vmcnt(0) lgkmcnt(0)
	v_lshlrev_b32_e32 v44, 16, v40
	v_and_b32_e32 v45, 0xffff0000, v40
	v_lshlrev_b32_e32 v40, 16, v41
	v_and_b32_e32 v41, 0xffff0000, v41
	v_lshlrev_b32_e32 v46, 16, v42
	v_and_b32_e32 v47, 0xffff0000, v42
	v_lshlrev_b32_e32 v42, 16, v43
	v_and_b32_e32 v43, 0xffff0000, v43
	v_pk_fma_f32 v[156:157], v[38:39], v[200:201], v[40:41]
	v_pk_fma_f32 v[154:155], v[36:37], v[198:199], v[44:45]
	v_pk_fma_f32 v[160:161], v[34:35], v[196:197], v[42:43]
	v_pk_fma_f32 v[158:159], v[32:33], v[194:195], v[46:47]
	v_lshl_add_u64 v[32:33], v[222:223], 1, s[0:1]
	ds_read_b128 v[32:35], v211 offset:4096
	s_waitcnt vmcnt(0) lgkmcnt(0)
	v_lshlrev_b32_e32 v36, 16, v32
	v_and_b32_e32 v37, 0xffff0000, v32
	v_lshlrev_b32_e32 v32, 16, v33
	v_and_b32_e32 v33, 0xffff0000, v33
	v_lshlrev_b32_e32 v38, 16, v34
	v_and_b32_e32 v39, 0xffff0000, v34
	v_lshlrev_b32_e32 v34, 16, v35
	v_and_b32_e32 v35, 0xffff0000, v35
	v_pk_fma_f32 v[164:165], v[30:31], v[200:201], v[32:33]
	v_pk_fma_f32 v[162:163], v[28:29], v[198:199], v[36:37]
	v_pk_fma_f32 v[168:169], v[26:27], v[196:197], v[34:35]
	v_pk_fma_f32 v[166:167], v[24:25], v[194:195], v[38:39]
	v_lshl_add_u64 v[24:25], v[220:221], 1, s[0:1]
	ds_read_b128 v[24:27], v211 offset:5120
	s_waitcnt vmcnt(0) lgkmcnt(0)
	v_lshlrev_b32_e32 v28, 16, v24
	v_and_b32_e32 v29, 0xffff0000, v24
	v_lshlrev_b32_e32 v24, 16, v25
	v_and_b32_e32 v25, 0xffff0000, v25
	v_lshlrev_b32_e32 v30, 16, v26
	v_and_b32_e32 v31, 0xffff0000, v26
	v_lshlrev_b32_e32 v26, 16, v27
	v_and_b32_e32 v27, 0xffff0000, v27
	v_pk_fma_f32 v[172:173], v[22:23], v[200:201], v[24:25]
	v_pk_fma_f32 v[170:171], v[20:21], v[198:199], v[28:29]
	v_pk_fma_f32 v[176:177], v[18:19], v[196:197], v[26:27]
	v_pk_fma_f32 v[174:175], v[16:17], v[194:195], v[30:31]
	v_lshl_add_u64 v[16:17], v[218:219], 1, s[0:1]
	ds_read_b128 v[16:19], v211 offset:6144
	s_waitcnt vmcnt(0) lgkmcnt(0)
	v_lshlrev_b32_e32 v20, 16, v16
	v_and_b32_e32 v21, 0xffff0000, v16
	v_lshlrev_b32_e32 v16, 16, v17
	v_and_b32_e32 v17, 0xffff0000, v17
	v_lshlrev_b32_e32 v22, 16, v18
	v_and_b32_e32 v23, 0xffff0000, v18
	v_lshlrev_b32_e32 v18, 16, v19
	v_and_b32_e32 v19, 0xffff0000, v19
	v_pk_fma_f32 v[180:181], v[14:15], v[200:201], v[16:17]
	v_pk_fma_f32 v[178:179], v[12:13], v[198:199], v[20:21]
	v_pk_fma_f32 v[184:185], v[10:11], v[196:197], v[18:19]
	v_pk_fma_f32 v[182:183], v[8:9], v[194:195], v[22:23]
	v_lshl_add_u64 v[8:9], v[216:217], 1, s[0:1]
	ds_read_b128 v[8:11], v211 offset:7168
	s_waitcnt vmcnt(0) lgkmcnt(0)
	v_lshlrev_b32_e32 v12, 16, v8
	v_and_b32_e32 v13, 0xffff0000, v8
	v_lshlrev_b32_e32 v8, 16, v9
	v_and_b32_e32 v9, 0xffff0000, v9
	v_lshlrev_b32_e32 v14, 16, v10
	v_and_b32_e32 v15, 0xffff0000, v10
	v_lshlrev_b32_e32 v10, 16, v11
	v_and_b32_e32 v11, 0xffff0000, v11
	v_pk_fma_f32 v[188:189], v[6:7], v[200:201], v[8:9]
	v_pk_fma_f32 v[186:187], v[4:5], v[198:199], v[12:13]
	v_pk_fma_f32 v[192:193], v[2:3], v[196:197], v[10:11]
	v_pk_fma_f32 v[190:191], v[0:1], v[194:195], v[14:15]
	s_nop 0

; __device__ __forceinline__ float bflo(unsigned w) { return __uint_as_float(w << 16); }
; __device__ __forceinline__ float bfhi(unsigned w) { return __uint_as_float(w & 0xffff0000u); }
;     __device__ __forceinline__ void fused(f32x4 (&acc)[2][2][4][2], const Unit& u, int wr, int wc, int fr, int fq, LAS unsigned char* lds, int wid, int lane) const {
;     ...
;             } else {
; #pragma unroll
;                 for (int ai = 0; ai < 2; ++ai)
; #pragma unroll
;                     for (int m = 0; m < 4; ++m) {
;                         const u32x4 xw = *(const u32x4*)(xin16 + (unsigned)((row0 + ai * 128 + m * 16) * DM + col));
;                         const f32x4 x0 = (f32x4){bflo(xw.x), bfhi(xw.x), bflo(xw.y), bfhi(xw.y)}, x1 = (f32x4){bflo(xw.z), bfhi(xw.z), bflo(xw.w), bfhi(xw.w)};
;                         acc[ai][bj][m][0] = x0 + g0 * acc[ai][bj][m][0]; acc[ai][bj][m][1] = x1 + g1 * acc[ai][bj][m][1];
.LBB0_410:
	v_lshrrev_b32_e32 v202, 6, v236
	v_and_b32_e32 v203, 63, v236
	s_nop 0
	v_readfirstlane_b32 s98, v202
	v_lshlrev_b32_e32 v203, 4, v203
	s_nop 3
	s_lshl_b32 s99, s98, 13
	s_add_i32 s99, s99, 0x2000
	v_add_u32_e32 v210, s99, v203
	s_cmp_eq_u32 s98, 7
	s_cselect_b32 s98, 0x200, 0
	s_add_i32 s98, s98, 0x10000
	s_add_i32 s98, s99, s98
	v_add_u32_e32 v211, s98, v203
	v_lshlrev_b32_e32 v202, 1, v64
	v_add_u32_e32 v203, 0x100, v202
	s_add_i32 m0, s99, 0x0
	s_nop 0
	global_load_lds_dwordx4 v202, s[0:1]
	s_add_i32 m0, s98, 0x0
	s_nop 0
	global_load_lds_dwordx4 v203, s[0:1]
	v_add_u32_e32 v202, 0x8000, v202
	v_add_u32_e32 v203, 0x8000, v203
	s_add_i32 m0, s99, 0x400
	s_nop 0
	global_load_lds_dwordx4 v202, s[0:1]
	s_add_i32 m0, s98, 0x400
	s_nop 0
	global_load_lds_dwordx4 v203, s[0:1]
	v_add_u32_e32 v202, 0x8000, v202
	v_add_u32_e32 v203, 0x8000, v203
	s_add_i32 m0, s99, 0x800
	s_nop 0
	global_load_lds_dwordx4 v202, s[0:1]
	s_add_i32 m0, s98, 0x800
	s_nop 0
	global_load_lds_dwordx4 v203, s[0:1]
	v_add_u32_e32 v202, 0x8000, v202
	v_add_u32_e32 v203, 0x8000, v203
	s_add_i32 m0, s99, 0xc00
	s_nop 0
	global_load_lds_dwordx4 v202, s[0:1]
	s_add_i32 m0, s98, 0xc00
	s_nop 0
	global_load_lds_dwordx4 v203, s[0:1]
	v_add_u32_e32 v202, 0x28000, v202
	v_add_u32_e32 v203, 0x28000, v203
	s_add_i32 m0, s99, 0x1000
	s_nop 0
	global_load_lds_dwordx4 v202, s[0:1]
	s_add_i32 m0, s98, 0x1000
	s_nop 0
	global_load_lds_dwordx4 v203, s[0:1]
	v_add_u32_e32 v202, 0x8000, v202
	v_add_u32_e32 v203, 0x8000, v203
	s_add_i32 m0, s99, 0x1400
	s_nop 0
	global_load_lds_dwordx4 v202, s[0:1]
	s_add_i32 m0, s98, 0x1400
	s_nop 0
	global_load_lds_dwordx4 v203, s[0:1]
	v_add_u32_e32 v202, 0x8000, v202
	v_add_u32_e32 v203, 0x8000, v203
	s_add_i32 m0, s99, 0x1800
	s_nop 0
	global_load_lds_dwordx4 v202, s[0:1]
	s_add_i32 m0, s98, 0x1800
	s_nop 0
	global_load_lds_dwordx4 v203, s[0:1]
	v_add_u32_e32 v202, 0x8000, v202
	v_add_u32_e32 v203, 0x8000, v203
	s_add_i32 m0, s99, 0x1c00
	s_nop 0
	global_load_lds_dwordx4 v202, s[0:1]
	s_add_i32 m0, s98, 0x1c00
	s_nop 0
	global_load_lds_dwordx4 v203, s[0:1]
	s_waitcnt vmcnt(0)
	s_branch .LBB0_295
